# v13 plus up GEMM (both layers): per-cluster s_setprio flips removed, one static s_setprio 1 for waves 4-7 before the K loop
# baseline (speedup 1.0000x reference)
; #define G8_STAGE(bufoff, gbase, voff) do { _Pragma("unroll") for (int _i = 0; _i < 2; ++_i) \
;     __builtin_amdgcn_global_load_lds((const unsigned*)((const char*)(gbase) + (voff)[_i]), (LAS unsigned*)(lds + (bufoff) + ldsw + _i * 8192), 16, 0, 0); } while (0)
; #define G8_LDA(dst, b, h) do { _Pragma("unroll") for (int m = 0; m < 4; ++m) _Pragma("unroll") for (int k = 0; k < 2; ++k) dst[m][k] = *(const LAS bf16x8*)(lds + G8_SA(b, h) + aoff + m * 2048 + k * 1024); } while (0)
; #define G8_LDB(dst, b, h) do { _Pragma("unroll") for (int n = 0; n < 2; ++n) _Pragma("unroll") for (int k = 0; k < 2; ++k) dst[n][k] = *(const LAS bf16x8*)(lds + G8_SB(b, h) + boff + n * 2048 + k * 1024); } while (0)
; #define G8_MMA(ai, bj, At, Bt) do { __builtin_amdgcn_s_setprio(1); _Pragma("unroll") for (int m = 0; m < 4; ++m) _Pragma("unroll") for (int n = 0; n < 2; ++n) _Pragma("unroll") for (int k = 0; k < 2; ++k) \
;     acc[ai][bj][m][n] = __builtin_amdgcn_mfma_f32_16x16x32_bf16(Bt[n][k], At[m][k], acc[ai][bj][m][n], 0, 0, 0); __builtin_amdgcn_s_setprio(0); } while (0)
; #define G8_WAIT_L(n) asm volatile("s_waitcnt lgkmcnt(" #n ")" ::: "memory")
; template <class Epi, class Sched>
; __device__ __forceinline__ void gemm_phase(LAS unsigned char* lds, const Gemm g, const Sched& S, const Epi& E) {
;     ...
;     const bool has_next = S.next(ui + 1, nxt);
;     const char* nA = has_next ? (const char*)g.A + (size_t)nxt.pm * tstepA + (size_t)nxt.koff * 2 : cA; const char* nB = has_next ? (const char*)g.Bt + (size_t)nxt.pn * tstepB + (size_t)nxt.koff * 2 : cB;
;     for (int t = 0; t < nt; t += 2) {
;       const bool last = (t == nt - 2);
;       const char* a1 = cA + (size_t)(t + 1) * kstep;
;       const char* a2 = last ? nA : cA + (size_t)(t + 2) * kstep; const char* b2 = last ? nB : cB + (size_t)(t + 2) * kstep;
;       const char* a3 = a2 + kstep; const char* b3 = b2 + kstep;
;       G8_LDB(B0, 0, 0); G8_SCHED; G8_LDA(At, 0, 0); G8_STAGE(G8_SA(1, 1), a1 + hstepA, voffA);
;       G8_WAIT_L(8); G8_BAR; G8_WAIT_L(0); G8_MMA(0, 0, At, B0); G8_BAR; G8_SCHED;
;     ...
; #pragma unroll
;     for (int a = 0; a < 2; ++a)
; #pragma unroll
;       for (int b = 0; b < 2; ++b)
; #pragma unroll
;         for (int m = 0; m < 4; ++m)
; #pragma unroll
;           for (int n = 0; n < 2; ++n) acc[a][b][m][n] = (f32x4){0.f, 0.f, 0.f, 0.f};
;     cur = nxt; cA = nA; cB = nB; ++ui;
.LBB0_2355:
	s_ashr_i32 s17, s16, 31
	v_cmp_lt_i64_e32 vcc, s[18:19], v[136:137]
	s_lshl_b64 s[18:19], s[16:17], 19
	s_add_u32 s18, s21, s18
	s_addc_u32 s19, s33, s19
	s_and_b64 s[28:29], vcc, exec
	s_cselect_b32 s17, s19, s31
	s_cselect_b32 s55, s18, s30
	s_ashr_i32 s15, s14, 31
	s_lshl_b64 s[28:29], s[14:15], 19
	s_add_u32 s28, s38, s28
	s_addc_u32 s29, s39, s29
	s_and_b64 s[36:37], vcc, exec
	s_cselect_b32 s15, s29, s35
	s_cselect_b32 s56, s28, s34
	s_add_u32 s30, s30, 0x40080
	s_addc_u32 s31, s31, 0
	s_add_u32 s57, s34, 0x100
	v_mov_b32_e32 v0, 0
	s_addc_u32 s58, s35, 0
	s_mov_b32 s59, -2
	v_mov_b32_e32 v1, v0
	v_mov_b32_e32 v2, v0
	v_mov_b32_e32 v3, v0
	v_mov_b32_e32 v4, v0
	v_mov_b32_e32 v5, v0
	v_mov_b32_e32 v6, v0
	v_mov_b32_e32 v7, v0
	v_mov_b32_e32 v16, v0
	v_mov_b32_e32 v17, v0
	v_mov_b32_e32 v18, v0
	v_mov_b32_e32 v19, v0
	v_mov_b32_e32 v20, v0
	v_mov_b32_e32 v21, v0
	v_mov_b32_e32 v22, v0
	v_mov_b32_e32 v23, v0
	s_waitcnt lgkmcnt(0)
	v_mov_b32_e32 v32, v0
	v_mov_b32_e32 v33, v0
	v_mov_b32_e32 v34, v0
	v_mov_b32_e32 v35, v0
	v_mov_b32_e32 v36, v0
	v_mov_b32_e32 v37, v0
	v_mov_b32_e32 v38, v0
	v_mov_b32_e32 v39, v0
	v_mov_b32_e32 v48, v0
	v_mov_b32_e32 v49, v0
	v_mov_b32_e32 v50, v0
	v_mov_b32_e32 v51, v0
	v_mov_b32_e32 v52, v0
	v_mov_b32_e32 v53, v0
	v_mov_b32_e32 v54, v0
	v_mov_b32_e32 v55, v0
	v_mov_b32_e32 v8, v0
	v_mov_b32_e32 v9, v0
	v_mov_b32_e32 v10, v0
	v_mov_b32_e32 v11, v0
	v_mov_b32_e32 v12, v0
	v_mov_b32_e32 v13, v0
	v_mov_b32_e32 v14, v0
	v_mov_b32_e32 v15, v0
	v_mov_b32_e32 v24, v0
	v_mov_b32_e32 v25, v0
	v_mov_b32_e32 v26, v0
	v_mov_b32_e32 v27, v0
	v_mov_b32_e32 v28, v0
	v_mov_b32_e32 v29, v0
	v_mov_b32_e32 v30, v0
	v_mov_b32_e32 v31, v0
	v_mov_b32_e32 v40, v0
	v_mov_b32_e32 v41, v0
	v_mov_b32_e32 v42, v0
	v_mov_b32_e32 v43, v0
	v_mov_b32_e32 v44, v0
	v_mov_b32_e32 v45, v0
	v_mov_b32_e32 v46, v0
	v_mov_b32_e32 v47, v0
	v_mov_b32_e32 v56, v0
	v_mov_b32_e32 v57, v0
	v_mov_b32_e32 v58, v0
	v_mov_b32_e32 v59, v0
	v_mov_b32_e32 v60, v0
	v_mov_b32_e32 v61, v0
	v_mov_b32_e32 v62, v0
	v_mov_b32_e32 v63, v0
	v_mov_b32_e32 v64, v0
	v_mov_b32_e32 v65, v0
	v_mov_b32_e32 v66, v0
	v_mov_b32_e32 v67, v0
	v_mov_b32_e32 v68, v0
	v_mov_b32_e32 v69, v0
	v_mov_b32_e32 v70, v0
	v_mov_b32_e32 v71, v0
	v_mov_b32_e32 v80, v0
	v_mov_b32_e32 v81, v0
	v_mov_b32_e32 v82, v0
	v_mov_b32_e32 v83, v0
	v_mov_b32_e32 v84, v0
	v_mov_b32_e32 v85, v0
	v_mov_b32_e32 v86, v0
	v_mov_b32_e32 v87, v0
	v_mov_b32_e32 v96, v0
	v_mov_b32_e32 v97, v0
	v_mov_b32_e32 v98, v0
	v_mov_b32_e32 v99, v0
	v_mov_b32_e32 v100, v0
	v_mov_b32_e32 v101, v0
	v_mov_b32_e32 v102, v0
	v_mov_b32_e32 v103, v0
	v_mov_b32_e32 v112, v0
	v_mov_b32_e32 v113, v0
	v_mov_b32_e32 v114, v0
	v_mov_b32_e32 v115, v0
	v_mov_b32_e32 v116, v0
	v_mov_b32_e32 v117, v0
	v_mov_b32_e32 v118, v0
	v_mov_b32_e32 v119, v0
	v_mov_b32_e32 v72, v0
	v_mov_b32_e32 v73, v0
	v_mov_b32_e32 v74, v0
	v_mov_b32_e32 v75, v0
	v_mov_b32_e32 v76, v0
	v_mov_b32_e32 v77, v0
	v_mov_b32_e32 v78, v0
	v_mov_b32_e32 v79, v0
	v_mov_b32_e32 v88, v0
	v_mov_b32_e32 v89, v0
	v_mov_b32_e32 v90, v0
	v_mov_b32_e32 v91, v0
	v_mov_b32_e32 v92, v0
	v_mov_b32_e32 v93, v0
	v_mov_b32_e32 v94, v0
	v_mov_b32_e32 v95, v0
	v_mov_b32_e32 v104, v0
	v_mov_b32_e32 v105, v0
	v_mov_b32_e32 v106, v0
	v_mov_b32_e32 v107, v0
	v_mov_b32_e32 v108, v0
	v_mov_b32_e32 v109, v0
	v_mov_b32_e32 v110, v0
	v_mov_b32_e32 v111, v0
	v_mov_b32_e32 v120, v0
	v_mov_b32_e32 v121, v0
	v_mov_b32_e32 v122, v0
	v_mov_b32_e32 v123, v0
	v_mov_b32_e32 v124, v0
	v_mov_b32_e32 v125, v0
	v_mov_b32_e32 v126, v0
	v_mov_b32_e32 v127, v0
	v_readfirstlane_b32 s98, v224
	s_nop 3
	s_lshr_b32 s98, s98, 6
	s_cmp_ge_u32 s98, 4
	s_cbranch_scc0 .Lprio0_done
	s_setprio 1
.Lprio0_done:
.LBB0_2356:
	ds_read_b128 v[148:151], v145
	ds_read_b128 v[152:155], v145 offset:1024
	ds_read_b128 v[156:159], v145 offset:2048
	ds_read_b128 v[160:163], v145 offset:3072
	s_add_u32 s34, s30, 0xfffc0080
	s_addc_u32 s35, s31, -1
	s_cmp_eq_u32 s59, 12
	s_cselect_b32 s37, s17, s35
	s_cselect_b32 s36, s55, s34
	s_cselect_b32 s35, s15, s58
	s_cselect_b32 s34, s56, s57
	v_lshl_add_u64 v[140:141], s[30:31], 0, v[132:133]
	s_add_i32 m0, s43, 0xc000
	ds_read_b128 v[164:167], v146
	ds_read_b128 v[168:171], v146 offset:1024
	ds_read_b128 v[172:175], v146 offset:2048
	ds_read_b128 v[176:179], v146 offset:3072
	ds_read_b128 v[180:183], v146 offset:4096
	ds_read_b128 v[184:187], v146 offset:5120
	ds_read_b128 v[188:191], v146 offset:6144
	ds_read_b128 v[192:195], v146 offset:7168
	global_load_lds_dwordx4 v[140:141], off
	v_lshl_add_u64 v[140:141], s[30:31], 0, v[134:135]
	s_add_i32 m0, s43, 0xe000
	s_nop 0
	global_load_lds_dwordx4 v[140:141], off
	s_waitcnt lgkmcnt(8)
	s_barrier
	s_waitcnt lgkmcnt(0)
	s_waitcnt lgkmcnt(0)
	v_mfma_f32_16x16x32_bf16 v[124:127], v[148:151], v[164:167], v[124:127]
	v_mfma_f32_16x16x32_bf16 v[120:123], v[156:159], v[164:167], v[120:123]
	v_mfma_f32_16x16x32_bf16 v[108:111], v[148:151], v[172:175], v[108:111]
	v_mfma_f32_16x16x32_bf16 v[104:107], v[156:159], v[172:175], v[104:107]
	v_mfma_f32_16x16x32_bf16 v[92:95], v[148:151], v[180:183], v[92:95]
	v_mfma_f32_16x16x32_bf16 v[88:91], v[156:159], v[180:183], v[88:91]
	v_mfma_f32_16x16x32_bf16 v[76:79], v[148:151], v[188:191], v[76:79]
	v_mfma_f32_16x16x32_bf16 v[72:75], v[156:159], v[188:191], v[72:75]
	v_mfma_f32_16x16x32_bf16 v[124:127], v[152:155], v[168:171], v[124:127]
	v_mfma_f32_16x16x32_bf16 v[120:123], v[160:163], v[168:171], v[120:123]
	v_mfma_f32_16x16x32_bf16 v[108:111], v[152:155], v[176:179], v[108:111]
	v_mfma_f32_16x16x32_bf16 v[104:107], v[160:163], v[176:179], v[104:107]
	v_mfma_f32_16x16x32_bf16 v[92:95], v[152:155], v[184:187], v[92:95]
	v_mfma_f32_16x16x32_bf16 v[88:91], v[160:163], v[184:187], v[88:91]
	v_mfma_f32_16x16x32_bf16 v[76:79], v[152:155], v[192:195], v[76:79]
	v_mfma_f32_16x16x32_bf16 v[72:75], v[160:163], v[192:195], v[72:75]
	s_barrier
; #define G8_STAGE(bufoff, gbase, voff) do { _Pragma("unroll") for (int _i = 0; _i < 2; ++_i) \
;     __builtin_amdgcn_global_load_lds((const unsigned*)((const char*)(gbase) + (voff)[_i]), (LAS unsigned*)(lds + (bufoff) + ldsw + _i * 8192), 16, 0, 0); } while (0)
; #define G8_LDA(dst, b, h) do { _Pragma("unroll") for (int m = 0; m < 4; ++m) _Pragma("unroll") for (int k = 0; k < 2; ++k) dst[m][k] = *(const LAS bf16x8*)(lds + G8_SA(b, h) + aoff + m * 2048 + k * 1024); } while (0)
; #define G8_LDB(dst, b, h) do { _Pragma("unroll") for (int n = 0; n < 2; ++n) _Pragma("unroll") for (int k = 0; k < 2; ++k) dst[n][k] = *(const LAS bf16x8*)(lds + G8_SB(b, h) + boff + n * 2048 + k * 1024); } while (0)
; #define G8_MMA(ai, bj, At, Bt) do { __builtin_amdgcn_s_setprio(1); _Pragma("unroll") for (int m = 0; m < 4; ++m) _Pragma("unroll") for (int n = 0; n < 2; ++n) _Pragma("unroll") for (int k = 0; k < 2; ++k) \
;     acc[ai][bj][m][n] = __builtin_amdgcn_mfma_f32_16x16x32_bf16(Bt[n][k], At[m][k], acc[ai][bj][m][n], 0, 0, 0); __builtin_amdgcn_s_setprio(0); } while (0)
; #define G8_WAIT_V(n) asm volatile("s_waitcnt vmcnt(" #n ")" ::: "memory")
; #define G8_WAIT_L(n) asm volatile("s_waitcnt lgkmcnt(" #n ")" ::: "memory")
; #define G8_BAR __builtin_amdgcn_s_barrier()
; #define G8_SCHED __builtin_amdgcn_sched_barrier(0)
; template <class Epi, class Sched>
; __device__ __forceinline__ void gemm_phase(LAS unsigned char* lds, const Gemm g, const Sched& S, const Epi& E) {
;     ...
;       G8_LDB(B1, 0, 1); G8_STAGE(G8_SB(0, 0), b2, voffB);
;       G8_BAR; G8_WAIT_L(0); G8_MMA(0, 1, At, B1); G8_BAR;
;       G8_LDA(At, 0, 1); G8_STAGE(G8_SA(0, 0), a2, voffA);
;       G8_BAR; G8_WAIT_L(0); G8_MMA(1, 0, At, B0); G8_BAR; G8_SCHED;
;       G8_STAGE(G8_SB(0, 1), b2 + hstepB, voffB);
;       G8_WAIT_V(6); G8_BAR; G8_MMA(1, 1, At, B1); G8_BAR;
;       G8_LDB(B0, 1, 0); G8_SCHED; G8_LDA(At, 1, 0); G8_STAGE(G8_SA(0, 1), a2 + hstepA, voffA);
	s_add_i32 s60, s52, s40
	v_lshl_add_u64 v[140:141], s[34:35], 0, v[130:131]
	s_mov_b32 m0, s60
	ds_read_b128 v[196:199], v147
	ds_read_b128 v[200:203], v147 offset:1024
	ds_read_b128 v[204:207], v147 offset:2048
	ds_read_b128 v[208:211], v147 offset:3072
	global_load_lds_dwordx4 v[140:141], off
	v_lshl_add_u64 v[212:213], s[34:35], 0, v[128:129]
	s_add_i32 m0, s60, 0x2000
	s_nop 0
	global_load_lds_dwordx4 v[212:213], off
	s_barrier
	s_waitcnt lgkmcnt(0)
	s_waitcnt lgkmcnt(0)
	v_mfma_f32_16x16x32_bf16 v[116:119], v[196:199], v[164:167], v[116:119]
	v_mfma_f32_16x16x32_bf16 v[112:115], v[204:207], v[164:167], v[112:115]
	v_mfma_f32_16x16x32_bf16 v[100:103], v[196:199], v[172:175], v[100:103]
	v_mfma_f32_16x16x32_bf16 v[96:99], v[204:207], v[172:175], v[96:99]
	v_mfma_f32_16x16x32_bf16 v[84:87], v[196:199], v[180:183], v[84:87]
	v_mfma_f32_16x16x32_bf16 v[80:83], v[204:207], v[180:183], v[80:83]
	v_mfma_f32_16x16x32_bf16 v[68:71], v[196:199], v[188:191], v[68:71]
	v_mfma_f32_16x16x32_bf16 v[64:67], v[204:207], v[188:191], v[64:67]
	v_mfma_f32_16x16x32_bf16 v[116:119], v[200:203], v[168:171], v[116:119]
	v_mfma_f32_16x16x32_bf16 v[112:115], v[208:211], v[168:171], v[112:115]
	v_mfma_f32_16x16x32_bf16 v[100:103], v[200:203], v[176:179], v[100:103]
	v_mfma_f32_16x16x32_bf16 v[96:99], v[208:211], v[176:179], v[96:99]
	v_mfma_f32_16x16x32_bf16 v[84:87], v[200:203], v[184:187], v[84:87]
	v_mfma_f32_16x16x32_bf16 v[80:83], v[208:211], v[184:187], v[80:83]
	v_mfma_f32_16x16x32_bf16 v[68:71], v[200:203], v[192:195], v[68:71]
	v_mfma_f32_16x16x32_bf16 v[64:67], v[208:211], v[192:195], v[64:67]
	s_mov_b32 m0, s43
	v_lshl_add_u64 v[214:215], s[36:37], 0, v[130:131]
	s_barrier
	ds_read_b128 v[164:167], v146 offset:16384
	ds_read_b128 v[168:171], v146 offset:17408
	ds_read_b128 v[172:175], v146 offset:18432
	ds_read_b128 v[176:179], v146 offset:19456
	ds_read_b128 v[180:183], v146 offset:20480
	ds_read_b128 v[184:187], v146 offset:21504
	ds_read_b128 v[188:191], v146 offset:22528
	ds_read_b128 v[192:195], v146 offset:23552
	global_load_lds_dwordx4 v[214:215], off
	v_lshl_add_u64 v[216:217], s[36:37], 0, v[128:129]
	s_mov_b32 m0, s44
	s_nop 0
	global_load_lds_dwordx4 v[216:217], off
	s_barrier
	s_waitcnt lgkmcnt(0)
	s_waitcnt lgkmcnt(0)
	v_mfma_f32_16x16x32_bf16 v[60:63], v[148:151], v[164:167], v[60:63]
	v_mfma_f32_16x16x32_bf16 v[56:59], v[156:159], v[164:167], v[56:59]
	v_mfma_f32_16x16x32_bf16 v[44:47], v[148:151], v[172:175], v[44:47]
	v_mfma_f32_16x16x32_bf16 v[40:43], v[156:159], v[172:175], v[40:43]
	v_mfma_f32_16x16x32_bf16 v[28:31], v[148:151], v[180:183], v[28:31]
	v_mfma_f32_16x16x32_bf16 v[24:27], v[156:159], v[180:183], v[24:27]
	v_mfma_f32_16x16x32_bf16 v[12:15], v[148:151], v[188:191], v[12:15]
	v_mfma_f32_16x16x32_bf16 v[8:11], v[156:159], v[188:191], v[8:11]
	v_mfma_f32_16x16x32_bf16 v[60:63], v[152:155], v[168:171], v[60:63]
	v_mfma_f32_16x16x32_bf16 v[56:59], v[160:163], v[168:171], v[56:59]
	v_mfma_f32_16x16x32_bf16 v[44:47], v[152:155], v[176:179], v[44:47]
	v_mfma_f32_16x16x32_bf16 v[40:43], v[160:163], v[176:179], v[40:43]
	v_mfma_f32_16x16x32_bf16 v[28:31], v[152:155], v[184:187], v[28:31]
	v_mfma_f32_16x16x32_bf16 v[24:27], v[160:163], v[184:187], v[24:27]
	v_mfma_f32_16x16x32_bf16 v[12:15], v[152:155], v[192:195], v[12:15]
	v_mfma_f32_16x16x32_bf16 v[8:11], v[160:163], v[192:195], v[8:11]
	s_barrier
	s_add_u32 s60, s34, 0x40000
	s_addc_u32 s61, s35, 0
	s_add_i32 s62, s53, s40
	v_lshl_add_u64 v[148:149], s[60:61], 0, v[130:131]
	s_mov_b32 m0, s62
	s_nop 0
	global_load_lds_dwordx4 v[148:149], off
	v_lshl_add_u64 v[148:149], s[60:61], 0, v[128:129]
	s_add_i32 m0, s62, 0x2000
	s_nop 0
	global_load_lds_dwordx4 v[148:149], off
	s_waitcnt vmcnt(6)
	s_barrier
	v_mfma_f32_16x16x32_bf16 v[52:55], v[196:199], v[164:167], v[52:55]
	v_mfma_f32_16x16x32_bf16 v[48:51], v[204:207], v[164:167], v[48:51]
	v_mfma_f32_16x16x32_bf16 v[36:39], v[196:199], v[172:175], v[36:39]
	v_mfma_f32_16x16x32_bf16 v[32:35], v[204:207], v[172:175], v[32:35]
	v_mfma_f32_16x16x32_bf16 v[20:23], v[196:199], v[180:183], v[20:23]
	v_mfma_f32_16x16x32_bf16 v[16:19], v[204:207], v[180:183], v[16:19]
	v_mfma_f32_16x16x32_bf16 v[4:7], v[196:199], v[188:191], v[4:7]
	v_mfma_f32_16x16x32_bf16 v[0:3], v[204:207], v[188:191], v[0:3]
	v_mfma_f32_16x16x32_bf16 v[52:55], v[200:203], v[168:171], v[52:55]
	v_mfma_f32_16x16x32_bf16 v[48:51], v[208:211], v[168:171], v[48:51]
	v_mfma_f32_16x16x32_bf16 v[36:39], v[200:203], v[176:179], v[36:39]
	v_mfma_f32_16x16x32_bf16 v[32:35], v[208:211], v[176:179], v[32:35]
	v_mfma_f32_16x16x32_bf16 v[20:23], v[200:203], v[184:187], v[20:23]
	v_mfma_f32_16x16x32_bf16 v[16:19], v[208:211], v[184:187], v[16:19]
	v_mfma_f32_16x16x32_bf16 v[4:7], v[200:203], v[192:195], v[4:7]
	v_mfma_f32_16x16x32_bf16 v[0:3], v[208:211], v[192:195], v[0:3]
	s_add_i32 s60, 0, 0x18000
	v_add_u32_e32 v160, s60, v143
	s_barrier
	ds_read_b128 v[148:151], v160
	ds_read_b128 v[152:155], v160 offset:1024
	ds_read_b128 v[156:159], v160 offset:2048
	ds_read_b128 v[160:163], v160 offset:3072
	s_add_u32 s36, s36, 0x40000
	s_addc_u32 s37, s37, 0
	s_mov_b32 m0, s45
	v_lshl_add_u64 v[196:197], s[36:37], 0, v[130:131]
	ds_read_b128 v[164:167], v146 offset:32768
	ds_read_b128 v[168:171], v146 offset:33792
	ds_read_b128 v[172:175], v146 offset:34816
	ds_read_b128 v[176:179], v146 offset:35840
	ds_read_b128 v[180:183], v146 offset:36864
	ds_read_b128 v[184:187], v146 offset:37888
	ds_read_b128 v[188:191], v146 offset:38912
	ds_read_b128 v[192:195], v146 offset:39936
	global_load_lds_dwordx4 v[196:197], off
	v_lshl_add_u64 v[196:197], s[36:37], 0, v[128:129]
	s_mov_b32 m0, s46
	s_nop 0
	global_load_lds_dwordx4 v[196:197], off
	s_waitcnt lgkmcnt(8)
	s_barrier
; #define G8_STAGE(bufoff, gbase, voff) do { _Pragma("unroll") for (int _i = 0; _i < 2; ++_i) \
;     __builtin_amdgcn_global_load_lds((const unsigned*)((const char*)(gbase) + (voff)[_i]), (LAS unsigned*)(lds + (bufoff) + ldsw + _i * 8192), 16, 0, 0); } while (0)
; #define G8_LDA(dst, b, h) do { _Pragma("unroll") for (int m = 0; m < 4; ++m) _Pragma("unroll") for (int k = 0; k < 2; ++k) dst[m][k] = *(const LAS bf16x8*)(lds + G8_SA(b, h) + aoff + m * 2048 + k * 1024); } while (0)
; #define G8_LDB(dst, b, h) do { _Pragma("unroll") for (int n = 0; n < 2; ++n) _Pragma("unroll") for (int k = 0; k < 2; ++k) dst[n][k] = *(const LAS bf16x8*)(lds + G8_SB(b, h) + boff + n * 2048 + k * 1024); } while (0)
; #define G8_MMA(ai, bj, At, Bt) do { __builtin_amdgcn_s_setprio(1); _Pragma("unroll") for (int m = 0; m < 4; ++m) _Pragma("unroll") for (int n = 0; n < 2; ++n) _Pragma("unroll") for (int k = 0; k < 2; ++k) \
;     acc[ai][bj][m][n] = __builtin_amdgcn_mfma_f32_16x16x32_bf16(Bt[n][k], At[m][k], acc[ai][bj][m][n], 0, 0, 0); __builtin_amdgcn_s_setprio(0); } while (0)
; #define G8_WAIT_V(n) asm volatile("s_waitcnt vmcnt(" #n ")" ::: "memory")
; #define G8_WAIT_L(n) asm volatile("s_waitcnt lgkmcnt(" #n ")" ::: "memory")
; #define G8_BAR __builtin_amdgcn_s_barrier()
; #define G8_SCHED __builtin_amdgcn_sched_barrier(0)
; template <class Epi, class Sched>
; __device__ __forceinline__ void gemm_phase(LAS unsigned char* lds, const Gemm g, const Sched& S, const Epi& E) {
;     ...
;       G8_WAIT_L(8); G8_BAR; G8_WAIT_L(0); G8_MMA(0, 0, At, B0); G8_BAR; G8_SCHED;
;       G8_LDB(B1, 1, 1); G8_STAGE(G8_SB(1, 0), b3, voffB);
;       G8_BAR; G8_WAIT_L(0); G8_MMA(0, 1, At, B1); G8_BAR;
;       G8_LDA(At, 1, 1); G8_STAGE(G8_SA(1, 0), a3, voffA);
;       G8_BAR; G8_WAIT_L(0); G8_MMA(1, 0, At, B0); G8_BAR; G8_SCHED;
;       G8_STAGE(G8_SB(1, 1), b3 + hstepB, voffB);
;       G8_WAIT_V(6); G8_BAR; G8_MMA(1, 1, At, B1); G8_BAR;
	s_waitcnt lgkmcnt(0)
	s_waitcnt lgkmcnt(0)
	v_mfma_f32_16x16x32_bf16 v[124:127], v[148:151], v[164:167], v[124:127]
	v_mfma_f32_16x16x32_bf16 v[120:123], v[156:159], v[164:167], v[120:123]
	v_mfma_f32_16x16x32_bf16 v[108:111], v[148:151], v[172:175], v[108:111]
	v_mfma_f32_16x16x32_bf16 v[104:107], v[156:159], v[172:175], v[104:107]
	v_mfma_f32_16x16x32_bf16 v[92:95], v[148:151], v[180:183], v[92:95]
	v_mfma_f32_16x16x32_bf16 v[88:91], v[156:159], v[180:183], v[88:91]
	v_mfma_f32_16x16x32_bf16 v[76:79], v[148:151], v[188:191], v[76:79]
	v_mfma_f32_16x16x32_bf16 v[72:75], v[156:159], v[188:191], v[72:75]
	v_mfma_f32_16x16x32_bf16 v[124:127], v[152:155], v[168:171], v[124:127]
	v_mfma_f32_16x16x32_bf16 v[120:123], v[160:163], v[168:171], v[120:123]
	v_mfma_f32_16x16x32_bf16 v[108:111], v[152:155], v[176:179], v[108:111]
	v_mfma_f32_16x16x32_bf16 v[104:107], v[160:163], v[176:179], v[104:107]
	v_mfma_f32_16x16x32_bf16 v[92:95], v[152:155], v[184:187], v[92:95]
	v_mfma_f32_16x16x32_bf16 v[88:91], v[160:163], v[184:187], v[88:91]
	v_mfma_f32_16x16x32_bf16 v[76:79], v[152:155], v[192:195], v[76:79]
	v_mfma_f32_16x16x32_bf16 v[72:75], v[160:163], v[192:195], v[72:75]
	s_barrier
	s_add_i32 s36, 0, 0x1c000
	s_add_i32 s37, s60, s40
	v_add_u32_e32 v208, s36, v143
	v_lshl_add_u64 v[140:141], v[140:141], 0, s[6:7]
	s_mov_b32 m0, s37
	ds_read_b128 v[196:199], v208
	ds_read_b128 v[200:203], v208 offset:1024
	ds_read_b128 v[204:207], v208 offset:2048
	ds_read_b128 v[208:211], v208 offset:3072
	global_load_lds_dwordx4 v[140:141], off
	v_lshl_add_u64 v[140:141], v[212:213], 0, s[6:7]
	s_add_i32 m0, s37, 0x2000
	s_nop 0
	global_load_lds_dwordx4 v[140:141], off
	s_barrier
	s_waitcnt lgkmcnt(0)
	s_waitcnt lgkmcnt(0)
	v_mfma_f32_16x16x32_bf16 v[116:119], v[196:199], v[164:167], v[116:119]
	v_mfma_f32_16x16x32_bf16 v[112:115], v[204:207], v[164:167], v[112:115]
	v_mfma_f32_16x16x32_bf16 v[100:103], v[196:199], v[172:175], v[100:103]
	v_mfma_f32_16x16x32_bf16 v[96:99], v[204:207], v[172:175], v[96:99]
	v_mfma_f32_16x16x32_bf16 v[84:87], v[196:199], v[180:183], v[84:87]
	v_mfma_f32_16x16x32_bf16 v[80:83], v[204:207], v[180:183], v[80:83]
	v_mfma_f32_16x16x32_bf16 v[68:71], v[196:199], v[188:191], v[68:71]
	v_mfma_f32_16x16x32_bf16 v[64:67], v[204:207], v[188:191], v[64:67]
	v_mfma_f32_16x16x32_bf16 v[116:119], v[200:203], v[168:171], v[116:119]
	v_mfma_f32_16x16x32_bf16 v[112:115], v[208:211], v[168:171], v[112:115]
	v_mfma_f32_16x16x32_bf16 v[100:103], v[200:203], v[176:179], v[100:103]
	v_mfma_f32_16x16x32_bf16 v[96:99], v[208:211], v[176:179], v[96:99]
	v_mfma_f32_16x16x32_bf16 v[84:87], v[200:203], v[184:187], v[84:87]
	v_mfma_f32_16x16x32_bf16 v[80:83], v[208:211], v[184:187], v[80:83]
	v_mfma_f32_16x16x32_bf16 v[68:71], v[200:203], v[192:195], v[68:71]
	v_mfma_f32_16x16x32_bf16 v[64:67], v[208:211], v[192:195], v[64:67]
	s_mov_b32 m0, s48
	v_lshl_add_u64 v[140:141], v[214:215], 0, s[6:7]
	s_barrier
	ds_read_b128 v[164:167], v146 offset:49152
	ds_read_b128 v[168:171], v146 offset:50176
	ds_read_b128 v[172:175], v146 offset:51200
	ds_read_b128 v[176:179], v146 offset:52224
	ds_read_b128 v[180:183], v146 offset:53248
	ds_read_b128 v[184:187], v146 offset:54272
	ds_read_b128 v[188:191], v146 offset:55296
	ds_read_b128 v[192:195], v146 offset:56320
	global_load_lds_dwordx4 v[140:141], off
	v_lshl_add_u64 v[140:141], v[216:217], 0, s[6:7]
	s_mov_b32 m0, s49
	s_nop 0
	global_load_lds_dwordx4 v[140:141], off
	s_barrier
	s_waitcnt lgkmcnt(0)
	s_waitcnt lgkmcnt(0)
	v_mfma_f32_16x16x32_bf16 v[60:63], v[148:151], v[164:167], v[60:63]
	v_mfma_f32_16x16x32_bf16 v[56:59], v[156:159], v[164:167], v[56:59]
	v_mfma_f32_16x16x32_bf16 v[44:47], v[148:151], v[172:175], v[44:47]
	v_mfma_f32_16x16x32_bf16 v[40:43], v[156:159], v[172:175], v[40:43]
	v_mfma_f32_16x16x32_bf16 v[28:31], v[148:151], v[180:183], v[28:31]
	v_mfma_f32_16x16x32_bf16 v[24:27], v[156:159], v[180:183], v[24:27]
	v_mfma_f32_16x16x32_bf16 v[12:15], v[148:151], v[188:191], v[12:15]
	v_mfma_f32_16x16x32_bf16 v[8:11], v[156:159], v[188:191], v[8:11]
	v_mfma_f32_16x16x32_bf16 v[60:63], v[152:155], v[168:171], v[60:63]
	v_mfma_f32_16x16x32_bf16 v[56:59], v[160:163], v[168:171], v[56:59]
	v_mfma_f32_16x16x32_bf16 v[44:47], v[152:155], v[176:179], v[44:47]
	v_mfma_f32_16x16x32_bf16 v[40:43], v[160:163], v[176:179], v[40:43]
	v_mfma_f32_16x16x32_bf16 v[28:31], v[152:155], v[184:187], v[28:31]
	v_mfma_f32_16x16x32_bf16 v[24:27], v[160:163], v[184:187], v[24:27]
	v_mfma_f32_16x16x32_bf16 v[12:15], v[152:155], v[192:195], v[12:15]
	v_mfma_f32_16x16x32_bf16 v[8:11], v[160:163], v[192:195], v[8:11]
	s_barrier
	s_add_u32 s34, s34, 0x40080
	s_addc_u32 s35, s35, 0
	s_add_i32 s36, s36, s40
	v_lshl_add_u64 v[140:141], s[34:35], 0, v[130:131]
	s_mov_b32 m0, s36
	s_nop 0
	global_load_lds_dwordx4 v[140:141], off
	v_lshl_add_u64 v[140:141], s[34:35], 0, v[128:129]
	s_add_i32 m0, s36, 0x2000
	s_nop 0
	global_load_lds_dwordx4 v[140:141], off
	s_waitcnt vmcnt(6)
	s_barrier
	v_mfma_f32_16x16x32_bf16 v[52:55], v[196:199], v[164:167], v[52:55]
	v_mfma_f32_16x16x32_bf16 v[48:51], v[204:207], v[164:167], v[48:51]
	v_mfma_f32_16x16x32_bf16 v[36:39], v[196:199], v[172:175], v[36:39]
	v_mfma_f32_16x16x32_bf16 v[32:35], v[204:207], v[172:175], v[32:35]
	v_mfma_f32_16x16x32_bf16 v[20:23], v[196:199], v[180:183], v[20:23]
	v_mfma_f32_16x16x32_bf16 v[16:19], v[204:207], v[180:183], v[16:19]
	v_mfma_f32_16x16x32_bf16 v[4:7], v[196:199], v[188:191], v[4:7]
	v_mfma_f32_16x16x32_bf16 v[0:3], v[204:207], v[188:191], v[0:3]
	v_mfma_f32_16x16x32_bf16 v[52:55], v[200:203], v[168:171], v[52:55]
	v_mfma_f32_16x16x32_bf16 v[48:51], v[208:211], v[168:171], v[48:51]
	v_mfma_f32_16x16x32_bf16 v[36:39], v[200:203], v[176:179], v[36:39]
	v_mfma_f32_16x16x32_bf16 v[32:35], v[208:211], v[176:179], v[32:35]
	v_mfma_f32_16x16x32_bf16 v[20:23], v[200:203], v[184:187], v[20:23]
	v_mfma_f32_16x16x32_bf16 v[16:19], v[208:211], v[184:187], v[16:19]
	v_mfma_f32_16x16x32_bf16 v[4:7], v[200:203], v[192:195], v[4:7]
	v_mfma_f32_16x16x32_bf16 v[0:3], v[208:211], v[192:195], v[0:3]
	s_add_i32 s59, s59, 2
	s_add_u32 s30, s30, 0x100
	s_addc_u32 s31, s31, 0
	s_add_u32 s57, s57, 0x100
	s_addc_u32 s58, s58, 0
	s_cmp_gt_u32 s59, 13
	s_barrier
; __device__ __forceinline__ float sigmoidf_(float x) { return __builtin_amdgcn_rcpf(1.f + __expf(-x)); }
;   __device__ __forceinline__ void operator()(const f32x4 (&acc)[2][2][4][2], const g8::Unit& u, int wr, int wc, int fr, int fq) const {
; #pragma unroll
;     for (int ai = 0; ai < 2; ++ai)
; #pragma unroll
;       for (int m = 0; m < 4; ++m) {
;         const int row = u.pm * 256 + ai * 128 + wr * 64 + m * 16 + fr;
; #pragma unroll
;         for (int bj = 0; bj < 2; ++bj) {
;           f32x4 v0 = acc[ai][bj][m][0], v1 = acc[ai][bj][m][1];
; #pragma unroll
;           for (int j = 0; j < 4; ++j) {
;             if (ACT == 1) { v0[j] = sigmoidf_(v0[j]); v1[j] = sigmoidf_(v1[j]); }
;             else { float a = fmaxf(v0[j], 0.f), b = fmaxf(v1[j], 0.f); v0[j] = a * a; v1[j] = b * b; }
;           }
;           const int c = u.pn * 256 + bj * 128 + wc * 32 + 8 * fq;
;           bfraw* dst = (c < split) ? (O0 + (size_t)row * ldc + c) : (O1 + (size_t)row * ldc + (c - split));
;           *(uint4*)dst = pack8v(v0, v1);
;         }
;       }
;   }
	s_cbranch_scc0 .LBB0_2356
	s_setprio 0
	v_max_f32_e32 v120, v120, v120
	v_max_f32_e32 v120, 0, v120
	v_mul_f32_e32 v157, v120, v120
	v_max_f32_e32 v120, v125, v125
	v_max_f32_e32 v121, v121, v121
	v_max_f32_e32 v120, 0, v120
	v_max_f32_e32 v121, 0, v121
	v_mul_f32_e32 v158, v120, v120
	v_mul_f32_e32 v159, v121, v121
	v_max_f32_e32 v120, v126, v126
	v_max_f32_e32 v121, v122, v122
	v_max_f32_e32 v120, 0, v120
	v_max_f32_e32 v121, 0, v121
	v_lshl_add_u32 v140, s4, 8, v142
	v_mul_f32_e32 v160, v120, v120
	v_mul_f32_e32 v126, v121, v121
	v_max_f32_e32 v120, v127, v127
	v_max_f32_e32 v121, v123, v123
	v_lshl_or_b32 v148, s5, 8, v144
	v_ashrrev_i32_e32 v141, 31, v140
	v_max_f32_e32 v124, v124, v124
	v_max_f32_e32 v120, 0, v120
	v_max_f32_e32 v121, 0, v121
	v_max_f32_e32 v124, 0, v124
	v_mul_f32_e32 v161, v120, v120
	v_mul_f32_e32 v127, v121, v121
	v_lshlrev_b64 v[120:121], 13, v[140:141]
	v_ashrrev_i32_e32 v149, 31, v148
	v_mul_f32_e32 v156, v124, v124
	v_lshl_add_u64 v[124:125], s[0:1], 0, v[120:121]
	v_lshlrev_b64 v[120:121], 1, v[148:149]
	v_mov_b32_e32 v149, v131
	v_lshlrev_b64 v[122:123], 1, v[148:149]
	v_lshl_add_u64 v[152:153], v[124:125], 0, v[122:123]
	v_lshl_add_u64 v[150:151], v[124:125], 0, v[120:121]
	v_lshl_add_u64 v[124:125], v[152:153], 0, s[10:11]
	v_cmp_gt_i32_e32 vcc, 2.0, v148
	v_max_f32_e32 v112, v112, v112
	v_cvt_pk_bf16_f32 v127, v126, v127
	v_cndmask_b32_e32 v155, v125, v151, vcc
	v_cndmask_b32_e32 v154, v124, v150, vcc
	v_cvt_pk_bf16_f32 v126, v157, v159
	v_cvt_pk_bf16_f32 v125, v160, v161
	v_cvt_pk_bf16_f32 v124, v156, v158
	v_max_f32_e32 v112, 0, v112
	global_store_dwordx4 v[154:155], v[124:127], off
	v_max_f32_e32 v113, v113, v113
	v_max_f32_e32 v113, 0, v113
	v_mul_f32_e32 v125, v112, v112
	v_max_f32_e32 v112, v117, v117
	v_max_f32_e32 v112, 0, v112
	v_mul_f32_e32 v126, v112, v112
	v_mul_f32_e32 v127, v113, v113
	v_max_f32_e32 v112, v118, v118
	v_max_f32_e32 v113, v114, v114
	v_max_f32_e32 v116, v116, v116
	v_max_f32_e32 v112, 0, v112
	v_max_f32_e32 v113, 0, v113
	v_max_f32_e32 v116, 0, v116
	v_mul_f32_e32 v118, v112, v112
	v_mul_f32_e32 v141, v113, v113
	v_max_f32_e32 v112, v119, v119
	v_max_f32_e32 v113, v115, v115
	v_mul_f32_e32 v124, v116, v116
	v_max_f32_e32 v112, 0, v112
	v_max_f32_e32 v113, 0, v113
	v_or_b32_e32 v116, 0x80, v148
	v_mul_f32_e32 v119, v112, v112
	v_mul_f32_e32 v149, v113, v113
	v_lshl_add_u64 v[112:113], v[150:151], 0, s[8:9]
	v_lshl_add_u64 v[114:115], v[152:153], 0, s[12:13]
	v_cmp_gt_i32_e64 s[4:5], 2.0, v116
	v_max_f32_e32 v104, v104, v104
	v_max_f32_e32 v104, 0, v104
	v_cndmask_b32_e64 v117, v115, v113, s[4:5]
	v_cndmask_b32_e64 v116, v114, v112, s[4:5]
	v_cvt_pk_bf16_f32 v115, v141, v149
	v_cvt_pk_bf16_f32 v114, v125, v127
	v_cvt_pk_bf16_f32 v113, v118, v119
	v_cvt_pk_bf16_f32 v112, v124, v126
	global_store_dwordx4 v[116:117], v[112:115], off
	v_max_f32_e32 v105, v105, v105
	v_max_f32_e32 v105, 0, v105
	v_mul_f32_e32 v115, v104, v104
	v_max_f32_e32 v104, v109, v109
	v_max_f32_e32 v104, 0, v104
	v_mul_f32_e32 v116, v104, v104
	v_mul_f32_e32 v117, v105, v105
	v_max_f32_e32 v104, v110, v110
	v_max_f32_e32 v105, v106, v106
	v_max_f32_e32 v104, 0, v104
	v_max_f32_e32 v105, 0, v105
	v_or_b32_e32 v112, 16, v140
	v_mul_f32_e32 v118, v104, v104
	v_mul_f32_e32 v106, v105, v105
	v_max_f32_e32 v104, v111, v111
	v_max_f32_e32 v105, v107, v107
	v_ashrrev_i32_e32 v113, 31, v112
	v_max_f32_e32 v104, 0, v104
	v_max_f32_e32 v105, 0, v105
	v_mul_f32_e32 v119, v104, v104
	v_mul_f32_e32 v107, v105, v105
	v_lshlrev_b64 v[104:105], 13, v[112:113]
	v_max_f32_e32 v108, v108, v108
	v_lshl_add_u64 v[104:105], s[0:1], 0, v[104:105]
	v_max_f32_e32 v108, 0, v108
	v_lshl_add_u64 v[110:111], v[104:105], 0, v[122:123]
	v_mul_f32_e32 v114, v108, v108
	v_lshl_add_u64 v[108:109], v[104:105], 0, v[120:121]
	v_lshl_add_u64 v[104:105], v[110:111], 0, s[10:11]
	v_max_f32_e32 v96, v96, v96
	v_cndmask_b32_e32 v113, v105, v109, vcc
	v_cndmask_b32_e32 v112, v104, v108, vcc
	v_cvt_pk_bf16_f32 v107, v106, v107
	v_cvt_pk_bf16_f32 v106, v115, v117
	v_cvt_pk_bf16_f32 v105, v118, v119
	v_cvt_pk_bf16_f32 v104, v114, v116
	v_max_f32_e32 v96, 0, v96
	global_store_dwordx4 v[112:113], v[104:107], off
	v_max_f32_e32 v97, v97, v97
	v_max_f32_e32 v97, 0, v97
	v_mul_f32_e32 v105, v96, v96
	v_max_f32_e32 v96, v101, v101
	v_max_f32_e32 v96, 0, v96
	v_mul_f32_e32 v106, v96, v96
	v_mul_f32_e32 v107, v97, v97
	v_max_f32_e32 v96, v102, v102
	v_max_f32_e32 v97, v98, v98
	v_max_f32_e32 v96, 0, v96
	v_max_f32_e32 v97, 0, v97
	v_max_f32_e32 v100, v100, v100
	v_mul_f32_e32 v102, v96, v96
	v_mul_f32_e32 v112, v97, v97
	v_max_f32_e32 v96, v103, v103
	v_max_f32_e32 v97, v99, v99
	v_max_f32_e32 v100, 0, v100
	v_max_f32_e32 v96, 0, v96
	v_max_f32_e32 v97, 0, v97
	v_mul_f32_e32 v104, v100, v100
	v_mul_f32_e32 v103, v96, v96
	v_mul_f32_e32 v113, v97, v97
	v_lshl_add_u64 v[96:97], v[108:109], 0, s[8:9]
	v_lshl_add_u64 v[98:99], v[110:111], 0, s[12:13]
	v_max_f32_e32 v88, v88, v88
	v_cndmask_b32_e64 v101, v99, v97, s[4:5]
	v_cndmask_b32_e64 v100, v98, v96, s[4:5]
	v_cvt_pk_bf16_f32 v99, v112, v113
	v_cvt_pk_bf16_f32 v98, v105, v107
	v_cvt_pk_bf16_f32 v97, v102, v103
	v_cvt_pk_bf16_f32 v96, v104, v106
	v_max_f32_e32 v88, 0, v88
	global_store_dwordx4 v[100:101], v[96:99], off
	v_max_f32_e32 v89, v89, v89
	v_max_f32_e32 v89, 0, v89
	v_mul_f32_e32 v99, v88, v88
	v_max_f32_e32 v88, v93, v93
	v_max_f32_e32 v88, 0, v88
	v_mul_f32_e32 v100, v88, v88
	v_mul_f32_e32 v101, v89, v89
	v_max_f32_e32 v88, v94, v94
	v_max_f32_e32 v89, v90, v90
	v_max_f32_e32 v88, 0, v88
	v_max_f32_e32 v89, 0, v89
	v_or_b32_e32 v96, 32, v140
	v_mul_f32_e32 v102, v88, v88
	v_mul_f32_e32 v90, v89, v89
; __device__ __forceinline__ float sigmoidf_(float x) { return __builtin_amdgcn_rcpf(1.f + __expf(-x)); }
;   __device__ __forceinline__ void operator()(const f32x4 (&acc)[2][2][4][2], const g8::Unit& u, int wr, int wc, int fr, int fq) const {
;     ...
;     for (int ai = 0; ai < 2; ++ai)
; #pragma unroll
;       for (int m = 0; m < 4; ++m) {
;         const int row = u.pm * 256 + ai * 128 + wr * 64 + m * 16 + fr;
; #pragma unroll
;         for (int bj = 0; bj < 2; ++bj) {
;           f32x4 v0 = acc[ai][bj][m][0], v1 = acc[ai][bj][m][1];
; #pragma unroll
;           for (int j = 0; j < 4; ++j) {
;             if (ACT == 1) { v0[j] = sigmoidf_(v0[j]); v1[j] = sigmoidf_(v1[j]); }
;             else { float a = fmaxf(v0[j], 0.f), b = fmaxf(v1[j], 0.f); v0[j] = a * a; v1[j] = b * b; }
;           }
;           const int c = u.pn * 256 + bj * 128 + wc * 32 + 8 * fq;
;           bfraw* dst = (c < split) ? (O0 + (size_t)row * ldc + c) : (O1 + (size_t)row * ldc + (c - split));
;           *(uint4*)dst = pack8v(v0, v1);
;         }
	v_max_f32_e32 v88, v95, v95
	v_max_f32_e32 v89, v91, v91
	v_ashrrev_i32_e32 v97, 31, v96
	v_max_f32_e32 v88, 0, v88
	v_max_f32_e32 v89, 0, v89
	v_mul_f32_e32 v103, v88, v88
	v_mul_f32_e32 v91, v89, v89
	v_lshlrev_b64 v[88:89], 13, v[96:97]
	v_max_f32_e32 v92, v92, v92
	v_lshl_add_u64 v[88:89], s[0:1], 0, v[88:89]
	v_max_f32_e32 v92, 0, v92
	v_lshl_add_u64 v[94:95], v[88:89], 0, v[122:123]
	v_mul_f32_e32 v98, v92, v92
	v_lshl_add_u64 v[92:93], v[88:89], 0, v[120:121]
	v_lshl_add_u64 v[88:89], v[94:95], 0, s[10:11]
	v_max_f32_e32 v80, v80, v80
	v_cndmask_b32_e32 v97, v89, v93, vcc
	v_cndmask_b32_e32 v96, v88, v92, vcc
	v_cvt_pk_bf16_f32 v91, v90, v91
	v_cvt_pk_bf16_f32 v90, v99, v101
	v_cvt_pk_bf16_f32 v89, v102, v103
	v_cvt_pk_bf16_f32 v88, v98, v100
	v_max_f32_e32 v80, 0, v80
	global_store_dwordx4 v[96:97], v[88:91], off
	v_max_f32_e32 v81, v81, v81
	v_max_f32_e32 v81, 0, v81
	v_mul_f32_e32 v89, v80, v80
	v_max_f32_e32 v80, v85, v85
	v_max_f32_e32 v80, 0, v80
	v_mul_f32_e32 v90, v80, v80
	v_mul_f32_e32 v91, v81, v81
	v_max_f32_e32 v80, v86, v86
	v_max_f32_e32 v81, v82, v82
	v_max_f32_e32 v80, 0, v80
	v_max_f32_e32 v81, 0, v81
	v_max_f32_e32 v84, v84, v84
	v_mul_f32_e32 v86, v80, v80
	v_mul_f32_e32 v96, v81, v81
	v_max_f32_e32 v80, v87, v87
	v_max_f32_e32 v81, v83, v83
	v_max_f32_e32 v84, 0, v84
	v_max_f32_e32 v80, 0, v80
	v_max_f32_e32 v81, 0, v81
	v_mul_f32_e32 v88, v84, v84
	v_mul_f32_e32 v87, v80, v80
	v_mul_f32_e32 v97, v81, v81
	v_lshl_add_u64 v[80:81], v[92:93], 0, s[8:9]
	v_lshl_add_u64 v[82:83], v[94:95], 0, s[12:13]
	v_max_f32_e32 v72, v72, v72
	v_cndmask_b32_e64 v85, v83, v81, s[4:5]
	v_cndmask_b32_e64 v84, v82, v80, s[4:5]
	v_cvt_pk_bf16_f32 v83, v96, v97
	v_cvt_pk_bf16_f32 v82, v89, v91
	v_cvt_pk_bf16_f32 v81, v86, v87
	v_cvt_pk_bf16_f32 v80, v88, v90
	v_max_f32_e32 v72, 0, v72
	global_store_dwordx4 v[84:85], v[80:83], off
	v_max_f32_e32 v73, v73, v73
	v_max_f32_e32 v73, 0, v73
	v_mul_f32_e32 v83, v72, v72
	v_max_f32_e32 v72, v77, v77
	v_max_f32_e32 v72, 0, v72
	v_mul_f32_e32 v84, v72, v72
	v_mul_f32_e32 v85, v73, v73
	v_max_f32_e32 v72, v78, v78
	v_max_f32_e32 v73, v74, v74
	v_max_f32_e32 v72, 0, v72
	v_max_f32_e32 v73, 0, v73
	v_or_b32_e32 v80, 48, v140
	v_mul_f32_e32 v86, v72, v72
	v_mul_f32_e32 v74, v73, v73
	v_max_f32_e32 v72, v79, v79
	v_max_f32_e32 v73, v75, v75
	v_ashrrev_i32_e32 v81, 31, v80
	v_max_f32_e32 v72, 0, v72
	v_max_f32_e32 v73, 0, v73
	v_mul_f32_e32 v87, v72, v72
	v_mul_f32_e32 v75, v73, v73
	v_lshlrev_b64 v[72:73], 13, v[80:81]
	v_max_f32_e32 v76, v76, v76
	v_lshl_add_u64 v[72:73], s[0:1], 0, v[72:73]
	v_max_f32_e32 v76, 0, v76
	v_lshl_add_u64 v[78:79], v[72:73], 0, v[122:123]
	v_mul_f32_e32 v82, v76, v76
	v_lshl_add_u64 v[76:77], v[72:73], 0, v[120:121]
	v_lshl_add_u64 v[72:73], v[78:79], 0, s[10:11]
	v_max_f32_e32 v64, v64, v64
	v_cndmask_b32_e32 v81, v73, v77, vcc
	v_cndmask_b32_e32 v80, v72, v76, vcc
	v_cvt_pk_bf16_f32 v75, v74, v75
	v_cvt_pk_bf16_f32 v74, v83, v85
	v_cvt_pk_bf16_f32 v73, v86, v87
	v_cvt_pk_bf16_f32 v72, v82, v84
	v_max_f32_e32 v64, 0, v64
	global_store_dwordx4 v[80:81], v[72:75], off
	v_max_f32_e32 v65, v65, v65
	v_max_f32_e32 v65, 0, v65
	v_mul_f32_e32 v73, v64, v64
	v_max_f32_e32 v64, v69, v69
	v_max_f32_e32 v64, 0, v64
	v_mul_f32_e32 v74, v64, v64
	v_mul_f32_e32 v75, v65, v65
	v_max_f32_e32 v64, v70, v70
	v_max_f32_e32 v65, v66, v66
	v_max_f32_e32 v64, 0, v64
	v_max_f32_e32 v65, 0, v65
	v_max_f32_e32 v68, v68, v68
	v_mul_f32_e32 v70, v64, v64
	v_mul_f32_e32 v80, v65, v65
	v_max_f32_e32 v64, v71, v71
	v_max_f32_e32 v65, v67, v67
	v_max_f32_e32 v68, 0, v68
	v_max_f32_e32 v64, 0, v64
	v_max_f32_e32 v65, 0, v65
	v_mul_f32_e32 v72, v68, v68
	v_mul_f32_e32 v71, v64, v64
	v_mul_f32_e32 v81, v65, v65
	v_lshl_add_u64 v[64:65], v[76:77], 0, s[8:9]
	v_lshl_add_u64 v[66:67], v[78:79], 0, s[12:13]
	v_max_f32_e32 v56, v56, v56
	v_cndmask_b32_e64 v69, v67, v65, s[4:5]
	v_cndmask_b32_e64 v68, v66, v64, s[4:5]
	v_cvt_pk_bf16_f32 v67, v80, v81
	v_cvt_pk_bf16_f32 v66, v73, v75
	v_cvt_pk_bf16_f32 v65, v70, v71
	v_cvt_pk_bf16_f32 v64, v72, v74
	v_max_f32_e32 v56, 0, v56
	global_store_dwordx4 v[68:69], v[64:67], off
	v_max_f32_e32 v57, v57, v57
	v_max_f32_e32 v57, 0, v57
	v_mul_f32_e32 v67, v56, v56
	v_max_f32_e32 v56, v61, v61
	v_max_f32_e32 v56, 0, v56
	v_mul_f32_e32 v68, v56, v56
	v_mul_f32_e32 v69, v57, v57
	v_max_f32_e32 v56, v62, v62
	v_max_f32_e32 v57, v58, v58
	v_max_f32_e32 v56, 0, v56
	v_max_f32_e32 v57, 0, v57
	v_add_u32_e32 v64, 0x80, v140
	v_mul_f32_e32 v70, v56, v56
	v_mul_f32_e32 v58, v57, v57
	v_max_f32_e32 v56, v63, v63
	v_max_f32_e32 v57, v59, v59
	v_ashrrev_i32_e32 v65, 31, v64
	v_max_f32_e32 v56, 0, v56
	v_max_f32_e32 v57, 0, v57
	v_mul_f32_e32 v71, v56, v56
	v_mul_f32_e32 v59, v57, v57
	v_lshlrev_b64 v[56:57], 13, v[64:65]
	v_max_f32_e32 v60, v60, v60
	v_lshl_add_u64 v[56:57], s[0:1], 0, v[56:57]
	v_max_f32_e32 v60, 0, v60
	v_lshl_add_u64 v[62:63], v[56:57], 0, v[122:123]
	v_mul_f32_e32 v66, v60, v60
	v_lshl_add_u64 v[60:61], v[56:57], 0, v[120:121]
	v_lshl_add_u64 v[56:57], v[62:63], 0, s[10:11]
	v_max_f32_e32 v48, v48, v48
	v_cndmask_b32_e32 v65, v57, v61, vcc
	v_cndmask_b32_e32 v64, v56, v60, vcc
	v_cvt_pk_bf16_f32 v59, v58, v59
	v_cvt_pk_bf16_f32 v58, v67, v69
	v_cvt_pk_bf16_f32 v57, v70, v71
	v_cvt_pk_bf16_f32 v56, v66, v68
	v_max_f32_e32 v48, 0, v48
	global_store_dwordx4 v[64:65], v[56:59], off
	v_max_f32_e32 v49, v49, v49
	v_max_f32_e32 v49, 0, v49
	v_mul_f32_e32 v57, v48, v48
	v_max_f32_e32 v48, v53, v53
	v_max_f32_e32 v48, 0, v48
	v_mul_f32_e32 v58, v48, v48
	v_mul_f32_e32 v59, v49, v49
	v_max_f32_e32 v48, v54, v54
	v_max_f32_e32 v49, v50, v50
	v_max_f32_e32 v48, 0, v48
; __device__ __forceinline__ float sigmoidf_(float x) { return __builtin_amdgcn_rcpf(1.f + __expf(-x)); }
;   __device__ __forceinline__ void operator()(const f32x4 (&acc)[2][2][4][2], const g8::Unit& u, int wr, int wc, int fr, int fq) const {
;     ...
;     for (int ai = 0; ai < 2; ++ai)
; #pragma unroll
;       for (int m = 0; m < 4; ++m) {
;         const int row = u.pm * 256 + ai * 128 + wr * 64 + m * 16 + fr;
; #pragma unroll
;         for (int bj = 0; bj < 2; ++bj) {
;           f32x4 v0 = acc[ai][bj][m][0], v1 = acc[ai][bj][m][1];
; #pragma unroll
;           for (int j = 0; j < 4; ++j) {
;             if (ACT == 1) { v0[j] = sigmoidf_(v0[j]); v1[j] = sigmoidf_(v1[j]); }
;             else { float a = fmaxf(v0[j], 0.f), b = fmaxf(v1[j], 0.f); v0[j] = a * a; v1[j] = b * b; }
;           }
;           const int c = u.pn * 256 + bj * 128 + wc * 32 + 8 * fq;
;           bfraw* dst = (c < split) ? (O0 + (size_t)row * ldc + c) : (O1 + (size_t)row * ldc + (c - split));
;           *(uint4*)dst = pack8v(v0, v1);
;         }
	v_max_f32_e32 v49, 0, v49
	v_max_f32_e32 v52, v52, v52
	v_mul_f32_e32 v54, v48, v48
	v_mul_f32_e32 v64, v49, v49
	v_max_f32_e32 v48, v55, v55
	v_max_f32_e32 v49, v51, v51
	v_max_f32_e32 v52, 0, v52
	v_max_f32_e32 v48, 0, v48
	v_max_f32_e32 v49, 0, v49
	v_mul_f32_e32 v56, v52, v52
	v_mul_f32_e32 v55, v48, v48
	v_mul_f32_e32 v65, v49, v49
	v_lshl_add_u64 v[48:49], v[60:61], 0, s[8:9]
	v_lshl_add_u64 v[50:51], v[62:63], 0, s[12:13]
	v_max_f32_e32 v40, v40, v40
	v_cndmask_b32_e64 v53, v51, v49, s[4:5]
	v_cndmask_b32_e64 v52, v50, v48, s[4:5]
	v_cvt_pk_bf16_f32 v51, v64, v65
	v_cvt_pk_bf16_f32 v50, v57, v59
	v_cvt_pk_bf16_f32 v49, v54, v55
	v_cvt_pk_bf16_f32 v48, v56, v58
	v_max_f32_e32 v40, 0, v40
	global_store_dwordx4 v[52:53], v[48:51], off
	v_max_f32_e32 v41, v41, v41
	v_max_f32_e32 v41, 0, v41
	v_mul_f32_e32 v51, v40, v40
	v_max_f32_e32 v40, v45, v45
	v_max_f32_e32 v40, 0, v40
	v_mul_f32_e32 v52, v40, v40
	v_mul_f32_e32 v53, v41, v41
	v_max_f32_e32 v40, v46, v46
	v_max_f32_e32 v41, v42, v42
	v_max_f32_e32 v40, 0, v40
	v_max_f32_e32 v41, 0, v41
	v_add_u32_e32 v48, 0x90, v140
	v_mul_f32_e32 v54, v40, v40
	v_mul_f32_e32 v42, v41, v41
	v_max_f32_e32 v40, v47, v47
	v_max_f32_e32 v41, v43, v43
	v_ashrrev_i32_e32 v49, 31, v48
	v_max_f32_e32 v40, 0, v40
	v_max_f32_e32 v41, 0, v41
	v_mul_f32_e32 v55, v40, v40
	v_mul_f32_e32 v43, v41, v41
	v_lshlrev_b64 v[40:41], 13, v[48:49]
	v_max_f32_e32 v44, v44, v44
	v_lshl_add_u64 v[40:41], s[0:1], 0, v[40:41]
	v_max_f32_e32 v44, 0, v44
	v_lshl_add_u64 v[46:47], v[40:41], 0, v[122:123]
	v_mul_f32_e32 v50, v44, v44
	v_lshl_add_u64 v[44:45], v[40:41], 0, v[120:121]
	v_lshl_add_u64 v[40:41], v[46:47], 0, s[10:11]
	v_max_f32_e32 v32, v32, v32
	v_cndmask_b32_e32 v49, v41, v45, vcc
	v_cndmask_b32_e32 v48, v40, v44, vcc
	v_cvt_pk_bf16_f32 v43, v42, v43
	v_cvt_pk_bf16_f32 v42, v51, v53
	v_cvt_pk_bf16_f32 v41, v54, v55
	v_cvt_pk_bf16_f32 v40, v50, v52
	v_max_f32_e32 v32, 0, v32
	global_store_dwordx4 v[48:49], v[40:43], off
	v_max_f32_e32 v33, v33, v33
	v_max_f32_e32 v33, 0, v33
	v_mul_f32_e32 v41, v32, v32
	v_max_f32_e32 v32, v37, v37
	v_max_f32_e32 v32, 0, v32
	v_mul_f32_e32 v42, v32, v32
	v_mul_f32_e32 v43, v33, v33
	v_max_f32_e32 v32, v38, v38
	v_max_f32_e32 v33, v34, v34
	v_max_f32_e32 v32, 0, v32
	v_max_f32_e32 v33, 0, v33
	v_max_f32_e32 v36, v36, v36
	v_mul_f32_e32 v38, v32, v32
	v_mul_f32_e32 v48, v33, v33
	v_max_f32_e32 v32, v39, v39
	v_max_f32_e32 v33, v35, v35
	v_max_f32_e32 v36, 0, v36
	v_max_f32_e32 v32, 0, v32
	v_max_f32_e32 v33, 0, v33
	v_mul_f32_e32 v40, v36, v36
	v_mul_f32_e32 v39, v32, v32
	v_mul_f32_e32 v49, v33, v33
	v_lshl_add_u64 v[32:33], v[44:45], 0, s[8:9]
	v_lshl_add_u64 v[34:35], v[46:47], 0, s[12:13]
	v_max_f32_e32 v24, v24, v24
	v_cndmask_b32_e64 v37, v35, v33, s[4:5]
	v_cndmask_b32_e64 v36, v34, v32, s[4:5]
	v_cvt_pk_bf16_f32 v35, v48, v49
	v_cvt_pk_bf16_f32 v34, v41, v43
	v_cvt_pk_bf16_f32 v33, v38, v39
	v_cvt_pk_bf16_f32 v32, v40, v42
	v_max_f32_e32 v24, 0, v24
	global_store_dwordx4 v[36:37], v[32:35], off
	v_max_f32_e32 v25, v25, v25
	v_max_f32_e32 v25, 0, v25
	v_mul_f32_e32 v35, v24, v24
	v_max_f32_e32 v24, v29, v29
	v_max_f32_e32 v24, 0, v24
	v_mul_f32_e32 v36, v24, v24
	v_mul_f32_e32 v37, v25, v25
	v_max_f32_e32 v24, v30, v30
	v_max_f32_e32 v25, v26, v26
	v_max_f32_e32 v24, 0, v24
	v_max_f32_e32 v25, 0, v25
	v_add_u32_e32 v32, 0xa0, v140
	v_mul_f32_e32 v38, v24, v24
	v_mul_f32_e32 v26, v25, v25
	v_max_f32_e32 v24, v31, v31
	v_max_f32_e32 v25, v27, v27
	v_ashrrev_i32_e32 v33, 31, v32
	v_max_f32_e32 v24, 0, v24
	v_max_f32_e32 v25, 0, v25
	v_mul_f32_e32 v39, v24, v24
	v_mul_f32_e32 v27, v25, v25
	v_lshlrev_b64 v[24:25], 13, v[32:33]
	v_max_f32_e32 v28, v28, v28
	v_lshl_add_u64 v[24:25], s[0:1], 0, v[24:25]
	v_max_f32_e32 v28, 0, v28
	v_lshl_add_u64 v[30:31], v[24:25], 0, v[122:123]
; __device__ __forceinline__ float sigmoidf_(float x) { return __builtin_amdgcn_rcpf(1.f + __expf(-x)); }
; #define G8_WAIT_V(n) asm volatile("s_waitcnt vmcnt(" #n ")" ::: "memory")
; #define G8_BAR __builtin_amdgcn_s_barrier()
; template <class Epi, class Sched>
; __device__ __forceinline__ void gemm_phase(LAS unsigned char* lds, const Gemm g, const Sched& S, const Epi& E) {
;     ...
;     E(acc, cur, wr, wc, fr, fq);
;     if (!has_next) break;
; #pragma unroll
;     for (int a = 0; a < 2; ++a)
; #pragma unroll
;       for (int b = 0; b < 2; ++b)
; #pragma unroll
;         for (int m = 0; m < 4; ++m)
; #pragma unroll
;           for (int n = 0; n < 2; ++n) acc[a][b][m][n] = (f32x4){0.f, 0.f, 0.f, 0.f};
;     cur = nxt; cA = nA; cB = nB; ++ui;
;   }
;   G8_WAIT_V(0);
;   if (wr == 0) G8_BAR;
;   __device__ __forceinline__ void operator()(const f32x4 (&acc)[2][2][4][2], const g8::Unit& u, int wr, int wc, int fr, int fq) const {
;     ...
;           for (int j = 0; j < 4; ++j) {
;             if (ACT == 1) { v0[j] = sigmoidf_(v0[j]); v1[j] = sigmoidf_(v1[j]); }
;             else { float a = fmaxf(v0[j], 0.f), b = fmaxf(v1[j], 0.f); v0[j] = a * a; v1[j] = b * b; }
;           }
;           const int c = u.pn * 256 + bj * 128 + wc * 32 + 8 * fq;
;           bfraw* dst = (c < split) ? (O0 + (size_t)row * ldc + c) : (O1 + (size_t)row * ldc + (c - split));
;           *(uint4*)dst = pack8v(v0, v1);
;         }
;       }
;   }
	v_mul_f32_e32 v34, v28, v28
	v_lshl_add_u64 v[28:29], v[24:25], 0, v[120:121]
	v_lshl_add_u64 v[24:25], v[30:31], 0, s[10:11]
	v_max_f32_e32 v16, v16, v16
	v_cndmask_b32_e32 v33, v25, v29, vcc
	v_cndmask_b32_e32 v32, v24, v28, vcc
	v_cvt_pk_bf16_f32 v27, v26, v27
	v_cvt_pk_bf16_f32 v26, v35, v37
	v_cvt_pk_bf16_f32 v25, v38, v39
	v_cvt_pk_bf16_f32 v24, v34, v36
	v_max_f32_e32 v16, 0, v16
	global_store_dwordx4 v[32:33], v[24:27], off
	v_max_f32_e32 v17, v17, v17
	v_max_f32_e32 v17, 0, v17
	v_mul_f32_e32 v25, v16, v16
	v_max_f32_e32 v16, v21, v21
	v_max_f32_e32 v16, 0, v16
	v_mul_f32_e32 v26, v16, v16
	v_mul_f32_e32 v27, v17, v17
	v_max_f32_e32 v16, v22, v22
	v_max_f32_e32 v17, v18, v18
	v_max_f32_e32 v16, 0, v16
	v_max_f32_e32 v17, 0, v17
	v_max_f32_e32 v20, v20, v20
	v_mul_f32_e32 v22, v16, v16
	v_mul_f32_e32 v32, v17, v17
	v_max_f32_e32 v16, v23, v23
	v_max_f32_e32 v17, v19, v19
	v_max_f32_e32 v20, 0, v20
	v_max_f32_e32 v16, 0, v16
	v_max_f32_e32 v17, 0, v17
	v_mul_f32_e32 v24, v20, v20
	v_mul_f32_e32 v23, v16, v16
	v_mul_f32_e32 v33, v17, v17
	v_lshl_add_u64 v[16:17], v[28:29], 0, s[8:9]
	v_lshl_add_u64 v[18:19], v[30:31], 0, s[12:13]
	v_max_f32_e32 v8, v8, v8
	v_cndmask_b32_e64 v21, v19, v17, s[4:5]
	v_cndmask_b32_e64 v20, v18, v16, s[4:5]
	v_cvt_pk_bf16_f32 v19, v32, v33
	v_cvt_pk_bf16_f32 v18, v25, v27
	v_cvt_pk_bf16_f32 v17, v22, v23
	v_cvt_pk_bf16_f32 v16, v24, v26
	v_max_f32_e32 v8, 0, v8
	global_store_dwordx4 v[20:21], v[16:19], off
	v_max_f32_e32 v9, v9, v9
	v_max_f32_e32 v9, 0, v9
	v_mul_f32_e32 v19, v8, v8
	v_max_f32_e32 v8, v13, v13
	v_max_f32_e32 v8, 0, v8
	v_mul_f32_e32 v20, v8, v8
	v_mul_f32_e32 v21, v9, v9
	v_max_f32_e32 v8, v14, v14
	v_max_f32_e32 v9, v10, v10
	v_max_f32_e32 v8, 0, v8
	v_max_f32_e32 v9, 0, v9
	v_add_u32_e32 v16, 0xb0, v140
	v_mul_f32_e32 v22, v8, v8
	v_mul_f32_e32 v10, v9, v9
	v_max_f32_e32 v8, v15, v15
	v_max_f32_e32 v9, v11, v11
	v_ashrrev_i32_e32 v17, 31, v16
	v_max_f32_e32 v8, 0, v8
	v_max_f32_e32 v9, 0, v9
	v_mul_f32_e32 v23, v8, v8
	v_mul_f32_e32 v11, v9, v9
	v_lshlrev_b64 v[8:9], 13, v[16:17]
	v_max_f32_e32 v12, v12, v12
	v_lshl_add_u64 v[8:9], s[0:1], 0, v[8:9]
	v_max_f32_e32 v12, 0, v12
	v_lshl_add_u64 v[14:15], v[8:9], 0, v[122:123]
	v_mul_f32_e32 v18, v12, v12
	v_lshl_add_u64 v[12:13], v[8:9], 0, v[120:121]
	v_lshl_add_u64 v[8:9], v[14:15], 0, s[10:11]
	v_max_f32_e32 v3, v3, v3
	v_max_f32_e32 v7, v7, v7
	v_max_f32_e32 v0, v0, v0
	v_max_f32_e32 v1, v1, v1
	v_max_f32_e32 v2, v2, v2
	v_max_f32_e32 v4, v4, v4
	v_max_f32_e32 v5, v5, v5
	v_max_f32_e32 v6, v6, v6
	v_cndmask_b32_e32 v17, v9, v13, vcc
	v_cndmask_b32_e32 v16, v8, v12, vcc
	v_cvt_pk_bf16_f32 v11, v10, v11
	v_cvt_pk_bf16_f32 v10, v19, v21
	v_cvt_pk_bf16_f32 v9, v22, v23
	v_cvt_pk_bf16_f32 v8, v18, v20
	v_max_f32_e32 v3, 0, v3
	v_max_f32_e32 v7, 0, v7
	v_max_f32_e32 v0, 0, v0
	v_max_f32_e32 v1, 0, v1
	v_max_f32_e32 v2, 0, v2
	v_max_f32_e32 v4, 0, v4
	v_max_f32_e32 v5, 0, v5
	v_max_f32_e32 v6, 0, v6
	global_store_dwordx4 v[16:17], v[8:11], off
	v_mul_f32_e32 v3, v3, v3
	v_mul_f32_e32 v7, v7, v7
	v_lshl_add_u64 v[8:9], v[12:13], 0, s[8:9]
	v_lshl_add_u64 v[10:11], v[14:15], 0, s[12:13]
	v_mul_f32_e32 v0, v0, v0
	v_mul_f32_e32 v1, v1, v1
	v_mul_f32_e32 v2, v2, v2
	v_mul_f32_e32 v4, v4, v4
	v_mul_f32_e32 v5, v5, v5
	v_mul_f32_e32 v6, v6, v6
	v_cndmask_b32_e64 v9, v11, v9, s[4:5]
	v_cndmask_b32_e64 v8, v10, v8, s[4:5]
	v_cvt_pk_bf16_f32 v3, v2, v3
	v_cvt_pk_bf16_f32 v2, v0, v1
	v_cvt_pk_bf16_f32 v1, v6, v7
	v_cvt_pk_bf16_f32 v0, v4, v5
	s_and_b64 vcc, exec, s[2:3]
	s_mov_b32 s5, s14
	s_mov_b32 s4, s16
	s_mov_b64 s[34:35], s[28:29]
	s_mov_b64 s[30:31], s[18:19]
	global_store_dwordx4 v[8:9], v[0:3], off
	s_cbranch_vccz .LBB0_2353
	s_waitcnt vmcnt(0)
	s_cmpk_gt_u32 s20, 0xff
	s_cbranch_scc1 .LBB0_2360
	s_barrier

; template <class Epi, class Sched>
; __device__ __forceinline__ void gemm_phase(LAS unsigned char* lds, const Gemm g, const Sched& S, const Epi& E) {
;     ...
;     const bool has_next = S.next(ui + 1, nxt);
;     const char* nA = has_next ? (const char*)g.A + (size_t)nxt.pm * tstepA + (size_t)nxt.koff * 2 : cA; const char* nB = has_next ? (const char*)g.Bt + (size_t)nxt.pn * tstepB + (size_t)nxt.koff * 2 : cB;
;     ...
; #pragma unroll
;     for (int a = 0; a < 2; ++a)
; #pragma unroll
;       for (int b = 0; b < 2; ++b)
; #pragma unroll
;         for (int m = 0; m < 4; ++m)
; #pragma unroll
;           for (int n = 0; n < 2; ++n) acc[a][b][m][n] = (f32x4){0.f, 0.f, 0.f, 0.f};
;     cur = nxt; cA = nA; cB = nB; ++ui;
.LBB0_5113:
	s_ashr_i32 s17, s16, 31
	v_cmp_lt_i64_e32 vcc, s[18:19], v[136:137]
	s_lshl_b64 s[18:19], s[16:17], 19
	s_add_u32 s18, s21, s18
	s_addc_u32 s19, s33, s19
	s_and_b64 s[28:29], vcc, exec
	s_cselect_b32 s17, s19, s31
	s_cselect_b32 s55, s18, s30
	s_ashr_i32 s15, s14, 31
	s_lshl_b64 s[28:29], s[14:15], 19
	s_add_u32 s28, s38, s28
	s_addc_u32 s29, s39, s29
	s_and_b64 s[36:37], vcc, exec
	s_cselect_b32 s15, s29, s35
	s_cselect_b32 s56, s28, s34
	s_add_u32 s30, s30, 0x40080
	s_addc_u32 s31, s31, 0
	s_add_u32 s57, s34, 0x100
	v_mov_b32_e32 v0, 0
	s_addc_u32 s58, s35, 0
	s_mov_b32 s59, -2
	v_mov_b32_e32 v1, v0
	v_mov_b32_e32 v2, v0
	v_mov_b32_e32 v3, v0
	v_mov_b32_e32 v4, v0
	v_mov_b32_e32 v5, v0
	v_mov_b32_e32 v6, v0
	v_mov_b32_e32 v7, v0
	v_mov_b32_e32 v16, v0
	v_mov_b32_e32 v17, v0
	v_mov_b32_e32 v18, v0
	v_mov_b32_e32 v19, v0
	s_waitcnt lgkmcnt(0)
	v_mov_b32_e32 v20, v0
	v_mov_b32_e32 v21, v0
	v_mov_b32_e32 v22, v0
	v_mov_b32_e32 v23, v0
	v_mov_b32_e32 v32, v0
	v_mov_b32_e32 v33, v0
	v_mov_b32_e32 v34, v0
	v_mov_b32_e32 v35, v0
	v_mov_b32_e32 v36, v0
	v_mov_b32_e32 v37, v0
	v_mov_b32_e32 v38, v0
	v_mov_b32_e32 v39, v0
	v_mov_b32_e32 v48, v0
	v_mov_b32_e32 v49, v0
	v_mov_b32_e32 v50, v0
	v_mov_b32_e32 v51, v0
	v_mov_b32_e32 v52, v0
	v_mov_b32_e32 v53, v0
	v_mov_b32_e32 v54, v0
	v_mov_b32_e32 v55, v0
	v_mov_b32_e32 v8, v0
	v_mov_b32_e32 v9, v0
	v_mov_b32_e32 v10, v0
	v_mov_b32_e32 v11, v0
	v_mov_b32_e32 v12, v0
	v_mov_b32_e32 v13, v0
	v_mov_b32_e32 v14, v0
	v_mov_b32_e32 v15, v0
	v_mov_b32_e32 v24, v0
	v_mov_b32_e32 v25, v0
	v_mov_b32_e32 v26, v0
	v_mov_b32_e32 v27, v0
	v_mov_b32_e32 v28, v0
	v_mov_b32_e32 v29, v0
	v_mov_b32_e32 v30, v0
	v_mov_b32_e32 v31, v0
	v_mov_b32_e32 v40, v0
	v_mov_b32_e32 v41, v0
	v_mov_b32_e32 v42, v0
	v_mov_b32_e32 v43, v0
	v_mov_b32_e32 v44, v0
	v_mov_b32_e32 v45, v0
	v_mov_b32_e32 v46, v0
	v_mov_b32_e32 v47, v0
	v_mov_b32_e32 v56, v0
	v_mov_b32_e32 v57, v0
	v_mov_b32_e32 v58, v0
	v_mov_b32_e32 v59, v0
	v_mov_b32_e32 v60, v0
	v_mov_b32_e32 v61, v0
	v_mov_b32_e32 v62, v0
	v_mov_b32_e32 v63, v0
	v_mov_b32_e32 v64, v0
	v_mov_b32_e32 v65, v0
	v_mov_b32_e32 v66, v0
	v_mov_b32_e32 v67, v0
	v_mov_b32_e32 v68, v0
	v_mov_b32_e32 v69, v0
	v_mov_b32_e32 v70, v0
	v_mov_b32_e32 v71, v0
	v_mov_b32_e32 v80, v0
	v_mov_b32_e32 v81, v0
	v_mov_b32_e32 v82, v0
	v_mov_b32_e32 v83, v0
	v_mov_b32_e32 v84, v0
	v_mov_b32_e32 v85, v0
	v_mov_b32_e32 v86, v0
	v_mov_b32_e32 v87, v0
	v_mov_b32_e32 v96, v0
	v_mov_b32_e32 v97, v0
	v_mov_b32_e32 v98, v0
	v_mov_b32_e32 v99, v0
	v_mov_b32_e32 v100, v0
	v_mov_b32_e32 v101, v0
	v_mov_b32_e32 v102, v0
	v_mov_b32_e32 v103, v0
	v_mov_b32_e32 v112, v0
	v_mov_b32_e32 v113, v0
	v_mov_b32_e32 v114, v0
	v_mov_b32_e32 v115, v0
	v_mov_b32_e32 v116, v0
	v_mov_b32_e32 v117, v0
	v_mov_b32_e32 v118, v0
	v_mov_b32_e32 v119, v0
	v_mov_b32_e32 v72, v0
	v_mov_b32_e32 v73, v0
	v_mov_b32_e32 v74, v0
	v_mov_b32_e32 v75, v0
	v_mov_b32_e32 v76, v0
	v_mov_b32_e32 v77, v0
	v_mov_b32_e32 v78, v0
	v_mov_b32_e32 v79, v0
	v_mov_b32_e32 v88, v0
	v_mov_b32_e32 v89, v0
	v_mov_b32_e32 v90, v0
	v_mov_b32_e32 v91, v0
	v_mov_b32_e32 v92, v0
	v_mov_b32_e32 v93, v0
	v_mov_b32_e32 v94, v0
	v_mov_b32_e32 v95, v0
	v_mov_b32_e32 v104, v0
	v_mov_b32_e32 v105, v0
	v_mov_b32_e32 v106, v0
	v_mov_b32_e32 v107, v0
	v_mov_b32_e32 v108, v0
	v_mov_b32_e32 v109, v0
	v_mov_b32_e32 v110, v0
	v_mov_b32_e32 v111, v0
	v_mov_b32_e32 v120, v0
	v_mov_b32_e32 v121, v0
	v_mov_b32_e32 v122, v0
	v_mov_b32_e32 v123, v0
	v_mov_b32_e32 v124, v0
	v_mov_b32_e32 v125, v0
	v_mov_b32_e32 v126, v0
	v_mov_b32_e32 v127, v0
	v_readfirstlane_b32 s98, v224
	s_nop 3
	s_lshr_b32 s98, s98, 6
	s_cmp_ge_u32 s98, 4
	s_cbranch_scc0 .Lprio1_done
	s_setprio 1
